# hand-written lean epilogue for in-projection/gate GEMM tiles of kind plain and sigmoid (same arithmetic, exact sqrt+div rstd), compiled path kept for rotary and gelu tiles
# speedup vs baseline: 1.0154x; 1.0154x over previous
; template <class Epi, class Sched, bool ALIGN_EPI = false, bool SP2 = false>
; __device__ __forceinline__ void gemm_phase(PG8_LAS unsigned char* lds, const Gemm g, const Sched& S, const Epi& E) {
;     ...
;         const bool has_next = S.next(ui + 1, nxt);
;         const char* nA = has_next ? (const char*)g.A + (size_t)nxt.pm * tstepA : cA; const char* nB = has_next ? (const char*)g.Bt + (size_t)nxt.pn * tstepB : cB;
;     ...
; #pragma unroll
;         for (int a = 0; a < 2; ++a)
; #pragma unroll
;             for (int b = 0; b < 2; ++b)
; #pragma unroll
;                 for (int m = 0; m < 4; ++m)
; #pragma unroll
;                     for (int n = 0; n < 2; ++n) acc[a][b][m][n] = (f32x4){0.f, 0.f, 0.f, 0.f};
;         cur = nxt; cA = nA; cB = nB; ++ui;
.LBB0_692:
	s_ashr_i32 s17, s16, 31
	s_lshl_b64 s[2:3], s[16:17], 19
	s_add_u32 s66, s58, s2
	s_addc_u32 s67, s59, s3
	s_and_b64 s[2:3], s[0:1], exec
	s_cselect_b32 s17, s67, s5
	s_cselect_b32 s78, s66, s4
	s_ashr_i32 s15, s14, 31
	s_lshl_b64 s[2:3], s[14:15], 19
	s_add_u32 s82, s38, s2
	s_addc_u32 s83, s41, s3
	s_and_b64 s[2:3], s[0:1], exec
	s_cselect_b32 s15, s83, s85
	s_cselect_b32 s89, s82, s84
	s_add_u32 s90, s84, 0x100
	s_addc_u32 s91, s85, 0
	s_add_u32 s4, s4, 0x40080
	v_mov_b32_e32 v0, 0
	s_addc_u32 s5, s5, 0
	s_mov_b32 s92, -2
	v_mov_b32_e32 v1, v0
	v_mov_b32_e32 v2, v0
	v_mov_b32_e32 v3, v0
	v_mov_b32_e32 v4, v0
	v_mov_b32_e32 v5, v0
	v_mov_b32_e32 v6, v0
	v_mov_b32_e32 v7, v0
	v_mov_b32_e32 v16, v0
	v_mov_b32_e32 v17, v0
	v_mov_b32_e32 v18, v0
	v_mov_b32_e32 v19, v0
	v_mov_b32_e32 v20, v0
	v_mov_b32_e32 v21, v0
	v_mov_b32_e32 v22, v0
	v_mov_b32_e32 v23, v0
	v_mov_b32_e32 v32, v0
	v_mov_b32_e32 v33, v0
	v_mov_b32_e32 v34, v0
	v_mov_b32_e32 v35, v0
	v_mov_b32_e32 v36, v0
	v_mov_b32_e32 v37, v0
	v_mov_b32_e32 v38, v0
	v_mov_b32_e32 v39, v0
	v_mov_b32_e32 v48, v0
	v_mov_b32_e32 v49, v0
	v_mov_b32_e32 v50, v0
	v_mov_b32_e32 v51, v0
	v_mov_b32_e32 v52, v0
	v_mov_b32_e32 v53, v0
	v_mov_b32_e32 v54, v0
	v_mov_b32_e32 v55, v0
	v_mov_b32_e32 v8, v0
	v_mov_b32_e32 v9, v0
	v_mov_b32_e32 v10, v0
	v_mov_b32_e32 v11, v0
	v_mov_b32_e32 v12, v0
	v_mov_b32_e32 v13, v0
	v_mov_b32_e32 v14, v0
	v_mov_b32_e32 v15, v0
	v_mov_b32_e32 v24, v0
	v_mov_b32_e32 v25, v0
	v_mov_b32_e32 v26, v0
	v_mov_b32_e32 v27, v0
	v_mov_b32_e32 v28, v0
	v_mov_b32_e32 v29, v0
	v_mov_b32_e32 v30, v0
	v_mov_b32_e32 v31, v0
	v_mov_b32_e32 v40, v0
	v_mov_b32_e32 v41, v0
	v_mov_b32_e32 v42, v0
	v_mov_b32_e32 v43, v0
	v_mov_b32_e32 v44, v0
	v_mov_b32_e32 v45, v0
	v_mov_b32_e32 v46, v0
	v_mov_b32_e32 v47, v0
	v_mov_b32_e32 v56, v0
	v_mov_b32_e32 v57, v0
	v_mov_b32_e32 v58, v0
	v_mov_b32_e32 v59, v0
	v_mov_b32_e32 v60, v0
	v_mov_b32_e32 v61, v0
	v_mov_b32_e32 v62, v0
	v_mov_b32_e32 v63, v0
	s_waitcnt vmcnt(0)
	v_mov_b32_e32 v64, v0
	v_mov_b32_e32 v65, v0
	v_mov_b32_e32 v66, v0
	v_mov_b32_e32 v67, v0
	v_mov_b32_e32 v68, v0
	v_mov_b32_e32 v69, v0
	v_mov_b32_e32 v70, v0
	v_mov_b32_e32 v71, v0
	v_mov_b32_e32 v80, v0
	v_mov_b32_e32 v81, v0
	v_mov_b32_e32 v82, v0
	v_mov_b32_e32 v83, v0
	v_mov_b32_e32 v84, v0
	v_mov_b32_e32 v85, v0
	v_mov_b32_e32 v86, v0
	v_mov_b32_e32 v87, v0
	v_mov_b32_e32 v96, v0
	v_mov_b32_e32 v97, v0
	v_mov_b32_e32 v98, v0
	v_mov_b32_e32 v99, v0
	v_mov_b32_e32 v100, v0
	v_mov_b32_e32 v101, v0
	v_mov_b32_e32 v102, v0
	v_mov_b32_e32 v103, v0
	v_mov_b32_e32 v112, v0
	v_mov_b32_e32 v113, v0
	v_mov_b32_e32 v114, v0
	v_mov_b32_e32 v115, v0
	v_mov_b32_e32 v116, v0
	v_mov_b32_e32 v117, v0
	v_mov_b32_e32 v118, v0
	v_mov_b32_e32 v119, v0
	v_mov_b32_e32 v72, v0
	v_mov_b32_e32 v73, v0
	v_mov_b32_e32 v74, v0
	v_mov_b32_e32 v75, v0
	v_mov_b32_e32 v76, v0
	v_mov_b32_e32 v77, v0
	v_mov_b32_e32 v78, v0
	v_mov_b32_e32 v79, v0
	v_mov_b32_e32 v88, v0
	v_mov_b32_e32 v89, v0
	v_mov_b32_e32 v90, v0
	v_mov_b32_e32 v91, v0
	v_mov_b32_e32 v92, v0
	v_mov_b32_e32 v93, v0
	v_mov_b32_e32 v94, v0
	v_mov_b32_e32 v95, v0
	v_mov_b32_e32 v104, v0
	v_mov_b32_e32 v105, v0
	v_mov_b32_e32 v106, v0
	v_mov_b32_e32 v107, v0
	v_mov_b32_e32 v108, v0
	v_mov_b32_e32 v109, v0
	v_mov_b32_e32 v110, v0
	v_mov_b32_e32 v111, v0
	v_mov_b32_e32 v120, v0
	v_mov_b32_e32 v121, v0
	v_mov_b32_e32 v122, v0
	v_mov_b32_e32 v123, v0
	v_mov_b32_e32 v124, v0
	v_mov_b32_e32 v125, v0
	v_mov_b32_e32 v126, v0
	v_mov_b32_e32 v127, v0

; DI int lane_id_opaque() { int l; asm volatile("v_mbcnt_lo_u32_b32 %0, -1, 0\n\tv_mbcnt_hi_u32_b32 %0, -1, %0" : "=v"(l)); return l; }
;     DI void operator()(AccRef acc, const pg8::Unit& u, int wr, int wc, int, int) const {
;         const int lane_ = lane_id_opaque(), fr = lane_ & 15, fq = lane_ >> 4;
;         const int pn = u.pn;
;         const int kind = dummy ? 2 : (kind_force >= 0 ? kind_force : (pn < 6 ? (pn < 3 ? 0 : 1) : (pn < 15 ? 2 : (pn < 19 ? 3 : 4))));
;         const bool rot = (kind < 2) && ((wc & 1) == 0);
;         const float qs = (kind == 0) ? 0.125f : 1.0f;
;         EPI_PRELOAD_RSTD(ssq)
.Llean_F_entry:
	v_and_b32_e32 v136, 15, v226
	v_lshrrev_b32_e32 v137, 4, v226
	v_or_b32_e32 v136, s49, v136
	v_lshl_add_u32 v138, s6, 8, v136
	v_lshlrev_b32_e32 v140, 4, v137
	v_lshl_add_u32 v140, v138, 6, v140
	v_mov_b32_e32 v141, 0
	v_lshl_add_u64 v[142:143], s[26:27], 0, v[140:141]
	v_add_u32_e32 v140, 0x2000, v140
	v_lshl_add_u64 v[144:145], s[26:27], 0, v[140:141]
	global_load_dwordx4 v[72:75], v[142:143], off
	global_load_dwordx4 v[76:79], v[142:143], off offset:1024
	global_load_dwordx4 v[80:83], v[142:143], off offset:2048
	global_load_dwordx4 v[84:87], v[142:143], off offset:3072
	global_load_dwordx4 v[104:107], v[144:145], off
	global_load_dwordx4 v[108:111], v[144:145], off offset:1024
	global_load_dwordx4 v[112:115], v[144:145], off offset:2048
	global_load_dwordx4 v[116:119], v[144:145], off offset:3072
	v_mul_lo_u32 v146, v138, s39
	v_mov_b32_e32 v147, 0
	s_lshl_b32 s0, s14, 8
	s_add_i32 s0, s0, s20
	v_lshl_add_u32 v148, v137, 3, s0
	v_lshlrev_b32_e32 v148, 1, v148
	v_mov_b32_e32 v149, 0
	v_lshl_add_u64 v[146:147], v[146:147], 1, s[72:73]
	v_lshl_add_u64 v[146:147], v[146:147], 0, v[148:149]
	s_lshl_b32 s2, s39, 5
	s_mov_b32 s3, 0
	s_mul_i32 s0, s39, 0xa0
	s_mov_b32 s1, 0
	v_mov_b32_e32 v213, 0x260
	s_waitcnt vmcnt(0)
	v_add_f32_e32 v168, v72, v73
	v_add_f32_e32 v169, v74, v75
	v_add_f32_e32 v168, v168, v169
	v_add_f32_e32 v170, v76, v77
	v_add_f32_e32 v171, v78, v79
	v_add_f32_e32 v170, v170, v171
	v_add_f32_e32 v172, v80, v81
	v_add_f32_e32 v173, v82, v83
	v_add_f32_e32 v172, v172, v173
	v_add_f32_e32 v174, v84, v85
	v_add_f32_e32 v175, v86, v87
	v_add_f32_e32 v174, v174, v175
	v_add_f32_e32 v176, v104, v105
	v_add_f32_e32 v177, v106, v107
	v_add_f32_e32 v176, v176, v177
	v_add_f32_e32 v178, v108, v109
	v_add_f32_e32 v179, v110, v111
	v_add_f32_e32 v178, v178, v179
	v_add_f32_e32 v180, v112, v113
	v_add_f32_e32 v181, v114, v115
	v_add_f32_e32 v180, v180, v181
	v_add_f32_e32 v182, v116, v117
	v_add_f32_e32 v183, v118, v119
	v_add_f32_e32 v182, v182, v183
	ds_swizzle_b32 v169, v168 offset:swizzle(SWAP,16)
	ds_swizzle_b32 v171, v170 offset:swizzle(SWAP,16)
	ds_swizzle_b32 v173, v172 offset:swizzle(SWAP,16)
	ds_swizzle_b32 v175, v174 offset:swizzle(SWAP,16)
	ds_swizzle_b32 v177, v176 offset:swizzle(SWAP,16)
	ds_swizzle_b32 v179, v178 offset:swizzle(SWAP,16)
	ds_swizzle_b32 v181, v180 offset:swizzle(SWAP,16)
	ds_swizzle_b32 v183, v182 offset:swizzle(SWAP,16)
	s_waitcnt lgkmcnt(0)
	v_add_f32_e32 v168, v168, v169
	v_add_f32_e32 v170, v170, v171
	v_add_f32_e32 v172, v172, v173
	v_add_f32_e32 v174, v174, v175
	v_add_f32_e32 v176, v176, v177
	v_add_f32_e32 v178, v178, v179
	v_add_f32_e32 v180, v180, v181
	v_add_f32_e32 v182, v182, v183
	v_mov_b32_e32 v169, v168
	v_mov_b32_e32 v171, v170
	v_mov_b32_e32 v173, v172
	v_mov_b32_e32 v175, v174
	v_mov_b32_e32 v177, v176
	v_mov_b32_e32 v179, v178
	v_mov_b32_e32 v181, v180
	v_mov_b32_e32 v183, v182
	s_nop 1
	v_permlane32_swap_b32_e32 v168, v169
	v_permlane32_swap_b32_e32 v170, v171
	v_permlane32_swap_b32_e32 v172, v173
	v_permlane32_swap_b32_e32 v174, v175
	v_permlane32_swap_b32_e32 v176, v177
	v_permlane32_swap_b32_e32 v178, v179
	v_permlane32_swap_b32_e32 v180, v181
	v_permlane32_swap_b32_e32 v182, v183
	v_add_f32_e32 v168, v168, v169
	v_add_f32_e32 v170, v170, v171
	v_add_f32_e32 v172, v172, v173
	v_add_f32_e32 v174, v174, v175
	v_add_f32_e32 v176, v176, v177
	v_add_f32_e32 v178, v178, v179
	v_add_f32_e32 v180, v180, v181
	v_add_f32_e32 v182, v182, v183
	v_fmamk_f32 v168, v168, 0x3a800000, v246
	v_cmp_gt_f32_e32 vcc, s33, v168
	v_mul_f32_e32 v208, 0x4f800000, v168
	s_nop 0
	v_cndmask_b32_e32 v168, v168, v208, vcc
	v_sqrt_f32_e32 v208, v168
	s_nop 0
	v_add_u32_e32 v209, -1, v208
	v_fma_f32 v210, -v209, v208, v168
	v_cmp_ge_f32_e64 s[98:99], 0, v210
	v_add_u32_e32 v210, 1, v208
	s_nop 0
	v_cndmask_b32_e64 v209, v208, v209, s[98:99]
	v_fma_f32 v208, -v210, v208, v168
	v_cmp_lt_f32_e64 s[98:99], 0, v208
	s_nop 1
	v_cndmask_b32_e64 v208, v209, v210, s[98:99]
	v_mul_f32_e32 v209, 0x37800000, v208
	v_cndmask_b32_e32 v208, v208, v209, vcc
	v_cmp_class_f32_e32 vcc, v168, v213
	s_nop 1
	v_cndmask_b32_e32 v168, v208, v168, vcc
	v_div_scale_f32 v208, s[98:99], v168, v168, 1.0
	v_rcp_f32_e32 v209, v208
	s_nop 0
	v_fma_f32 v210, -v208, v209, 1.0
	v_fmac_f32_e32 v209, v210, v209
	v_div_scale_f32 v210, vcc, 1.0, v168, 1.0
	v_mul_f32_e32 v211, v210, v209
	v_fma_f32 v212, -v208, v211, v210
	v_fmac_f32_e32 v211, v212, v209
	v_fma_f32 v208, -v208, v211, v210
	v_div_fmas_f32 v208, v208, v209, v211
	v_div_fixup_f32 v168, v208, v168, 1.0
	v_fmamk_f32 v170, v170, 0x3a800000, v246
	v_cmp_gt_f32_e32 vcc, s33, v170
	v_mul_f32_e32 v208, 0x4f800000, v170
	s_nop 0
	v_cndmask_b32_e32 v170, v170, v208, vcc
	v_sqrt_f32_e32 v208, v170
	s_nop 0
	v_add_u32_e32 v209, -1, v208
	v_fma_f32 v210, -v209, v208, v170
	v_cmp_ge_f32_e64 s[98:99], 0, v210
	v_add_u32_e32 v210, 1, v208
	s_nop 0
	v_cndmask_b32_e64 v209, v208, v209, s[98:99]
	v_fma_f32 v208, -v210, v208, v170
	v_cmp_lt_f32_e64 s[98:99], 0, v208
	s_nop 1
	v_cndmask_b32_e64 v208, v209, v210, s[98:99]
	v_mul_f32_e32 v209, 0x37800000, v208
	v_cndmask_b32_e32 v208, v208, v209, vcc
	v_cmp_class_f32_e32 vcc, v170, v213
	s_nop 1
	v_cndmask_b32_e32 v170, v208, v170, vcc
	v_div_scale_f32 v208, s[98:99], v170, v170, 1.0
	v_rcp_f32_e32 v209, v208
	s_nop 0
	v_fma_f32 v210, -v208, v209, 1.0
	v_fmac_f32_e32 v209, v210, v209
	v_div_scale_f32 v210, vcc, 1.0, v170, 1.0
	v_mul_f32_e32 v211, v210, v209
	v_fma_f32 v212, -v208, v211, v210
	v_fmac_f32_e32 v211, v212, v209
	v_fma_f32 v208, -v208, v211, v210
	v_div_fmas_f32 v208, v208, v209, v211
	v_div_fixup_f32 v170, v208, v170, 1.0
;     DI void operator()(AccRef acc, const pg8::Unit& u, int wr, int wc, int, int) const {
;     ...
;         const int kind = dummy ? 2 : (kind_force >= 0 ? kind_force : (pn < 6 ? (pn < 3 ? 0 : 1) : (pn < 15 ? 2 : (pn < 19 ? 3 : 4))));
	v_fmamk_f32 v172, v172, 0x3a800000, v246
	v_cmp_gt_f32_e32 vcc, s33, v172
	v_mul_f32_e32 v208, 0x4f800000, v172
	s_nop 0
	v_cndmask_b32_e32 v172, v172, v208, vcc
	v_sqrt_f32_e32 v208, v172
	s_nop 0
	v_add_u32_e32 v209, -1, v208
	v_fma_f32 v210, -v209, v208, v172
	v_cmp_ge_f32_e64 s[98:99], 0, v210
	v_add_u32_e32 v210, 1, v208
	s_nop 0
	v_cndmask_b32_e64 v209, v208, v209, s[98:99]
	v_fma_f32 v208, -v210, v208, v172
	v_cmp_lt_f32_e64 s[98:99], 0, v208
	s_nop 1
	v_cndmask_b32_e64 v208, v209, v210, s[98:99]
	v_mul_f32_e32 v209, 0x37800000, v208
	v_cndmask_b32_e32 v208, v208, v209, vcc
	v_cmp_class_f32_e32 vcc, v172, v213
	s_nop 1
	v_cndmask_b32_e32 v172, v208, v172, vcc
	v_div_scale_f32 v208, s[98:99], v172, v172, 1.0
	v_rcp_f32_e32 v209, v208
	s_nop 0
	v_fma_f32 v210, -v208, v209, 1.0
	v_fmac_f32_e32 v209, v210, v209
	v_div_scale_f32 v210, vcc, 1.0, v172, 1.0
	v_mul_f32_e32 v211, v210, v209
	v_fma_f32 v212, -v208, v211, v210
	v_fmac_f32_e32 v211, v212, v209
	v_fma_f32 v208, -v208, v211, v210
	v_div_fmas_f32 v208, v208, v209, v211
	v_div_fixup_f32 v172, v208, v172, 1.0
	v_fmamk_f32 v174, v174, 0x3a800000, v246
	v_cmp_gt_f32_e32 vcc, s33, v174
	v_mul_f32_e32 v208, 0x4f800000, v174
	s_nop 0
	v_cndmask_b32_e32 v174, v174, v208, vcc
	v_sqrt_f32_e32 v208, v174
	s_nop 0
	v_add_u32_e32 v209, -1, v208
	v_fma_f32 v210, -v209, v208, v174
	v_cmp_ge_f32_e64 s[98:99], 0, v210
	v_add_u32_e32 v210, 1, v208
	s_nop 0
	v_cndmask_b32_e64 v209, v208, v209, s[98:99]
	v_fma_f32 v208, -v210, v208, v174
	v_cmp_lt_f32_e64 s[98:99], 0, v208
	s_nop 1
	v_cndmask_b32_e64 v208, v209, v210, s[98:99]
	v_mul_f32_e32 v209, 0x37800000, v208
	v_cndmask_b32_e32 v208, v208, v209, vcc
	v_cmp_class_f32_e32 vcc, v174, v213
	s_nop 1
	v_cndmask_b32_e32 v174, v208, v174, vcc
	v_div_scale_f32 v208, s[98:99], v174, v174, 1.0
	v_rcp_f32_e32 v209, v208
	s_nop 0
	v_fma_f32 v210, -v208, v209, 1.0
	v_fmac_f32_e32 v209, v210, v209
	v_div_scale_f32 v210, vcc, 1.0, v174, 1.0
	v_mul_f32_e32 v211, v210, v209
	v_fma_f32 v212, -v208, v211, v210
	v_fmac_f32_e32 v211, v212, v209
	v_fma_f32 v208, -v208, v211, v210
	v_div_fmas_f32 v208, v208, v209, v211
	v_div_fixup_f32 v174, v208, v174, 1.0
	v_fmamk_f32 v176, v176, 0x3a800000, v246
	v_cmp_gt_f32_e32 vcc, s33, v176
	v_mul_f32_e32 v208, 0x4f800000, v176
	s_nop 0
	v_cndmask_b32_e32 v176, v176, v208, vcc
	v_sqrt_f32_e32 v208, v176
	s_nop 0
	v_add_u32_e32 v209, -1, v208
	v_fma_f32 v210, -v209, v208, v176
	v_cmp_ge_f32_e64 s[98:99], 0, v210
	v_add_u32_e32 v210, 1, v208
	s_nop 0
	v_cndmask_b32_e64 v209, v208, v209, s[98:99]
	v_fma_f32 v208, -v210, v208, v176
	v_cmp_lt_f32_e64 s[98:99], 0, v208
	s_nop 1
	v_cndmask_b32_e64 v208, v209, v210, s[98:99]
	v_mul_f32_e32 v209, 0x37800000, v208
	v_cndmask_b32_e32 v208, v208, v209, vcc
	v_cmp_class_f32_e32 vcc, v176, v213
	s_nop 1
	v_cndmask_b32_e32 v176, v208, v176, vcc
	v_div_scale_f32 v208, s[98:99], v176, v176, 1.0
	v_rcp_f32_e32 v209, v208
	s_nop 0
	v_fma_f32 v210, -v208, v209, 1.0
	v_fmac_f32_e32 v209, v210, v209
	v_div_scale_f32 v210, vcc, 1.0, v176, 1.0
	v_mul_f32_e32 v211, v210, v209
	v_fma_f32 v212, -v208, v211, v210
	v_fmac_f32_e32 v211, v212, v209
	v_fma_f32 v208, -v208, v211, v210
	v_div_fmas_f32 v208, v208, v209, v211
	v_div_fixup_f32 v176, v208, v176, 1.0
	v_fmamk_f32 v178, v178, 0x3a800000, v246
	v_cmp_gt_f32_e32 vcc, s33, v178
	v_mul_f32_e32 v208, 0x4f800000, v178
	s_nop 0
	v_cndmask_b32_e32 v178, v178, v208, vcc
	v_sqrt_f32_e32 v208, v178
	s_nop 0
	v_add_u32_e32 v209, -1, v208
	v_fma_f32 v210, -v209, v208, v178
	v_cmp_ge_f32_e64 s[98:99], 0, v210
	v_add_u32_e32 v210, 1, v208
	s_nop 0
	v_cndmask_b32_e64 v209, v208, v209, s[98:99]
	v_fma_f32 v208, -v210, v208, v178
	v_cmp_lt_f32_e64 s[98:99], 0, v208
	s_nop 1
	v_cndmask_b32_e64 v208, v209, v210, s[98:99]
	v_mul_f32_e32 v209, 0x37800000, v208
	v_cndmask_b32_e32 v208, v208, v209, vcc
	v_cmp_class_f32_e32 vcc, v178, v213
	s_nop 1
	v_cndmask_b32_e32 v178, v208, v178, vcc
	v_div_scale_f32 v208, s[98:99], v178, v178, 1.0
	v_rcp_f32_e32 v209, v208
	s_nop 0
	v_fma_f32 v210, -v208, v209, 1.0
	v_fmac_f32_e32 v209, v210, v209
	v_div_scale_f32 v210, vcc, 1.0, v178, 1.0
	v_mul_f32_e32 v211, v210, v209
	v_fma_f32 v212, -v208, v211, v210
	v_fmac_f32_e32 v211, v212, v209
	v_fma_f32 v208, -v208, v211, v210
	v_div_fmas_f32 v208, v208, v209, v211
	v_div_fixup_f32 v178, v208, v178, 1.0
	v_fmamk_f32 v180, v180, 0x3a800000, v246
	v_cmp_gt_f32_e32 vcc, s33, v180
	v_mul_f32_e32 v208, 0x4f800000, v180
	s_nop 0
	v_cndmask_b32_e32 v180, v180, v208, vcc
	v_sqrt_f32_e32 v208, v180
	s_nop 0
	v_add_u32_e32 v209, -1, v208
	v_fma_f32 v210, -v209, v208, v180
	v_cmp_ge_f32_e64 s[98:99], 0, v210
	v_add_u32_e32 v210, 1, v208
	s_nop 0
	v_cndmask_b32_e64 v209, v208, v209, s[98:99]
	v_fma_f32 v208, -v210, v208, v180
	v_cmp_lt_f32_e64 s[98:99], 0, v208
	s_nop 1
	v_cndmask_b32_e64 v208, v209, v210, s[98:99]
	v_mul_f32_e32 v209, 0x37800000, v208
	v_cndmask_b32_e32 v208, v208, v209, vcc
	v_cmp_class_f32_e32 vcc, v180, v213
	s_nop 1
	v_cndmask_b32_e32 v180, v208, v180, vcc
	v_div_scale_f32 v208, s[98:99], v180, v180, 1.0
	v_rcp_f32_e32 v209, v208
	s_nop 0
	v_fma_f32 v210, -v208, v209, 1.0
	v_fmac_f32_e32 v209, v210, v209
	v_div_scale_f32 v210, vcc, 1.0, v180, 1.0
	v_mul_f32_e32 v211, v210, v209
	v_fma_f32 v212, -v208, v211, v210
	v_fmac_f32_e32 v211, v212, v209
	v_fma_f32 v208, -v208, v211, v210
	v_div_fmas_f32 v208, v208, v209, v211
	v_div_fixup_f32 v180, v208, v180, 1.0
	v_fmamk_f32 v182, v182, 0x3a800000, v246
	v_cmp_gt_f32_e32 vcc, s33, v182
	v_mul_f32_e32 v208, 0x4f800000, v182
	s_nop 0
	v_cndmask_b32_e32 v182, v182, v208, vcc
	v_sqrt_f32_e32 v208, v182
	s_nop 0
	v_add_u32_e32 v209, -1, v208
	v_fma_f32 v210, -v209, v208, v182
	v_cmp_ge_f32_e64 s[98:99], 0, v210
	v_add_u32_e32 v210, 1, v208
	s_nop 0
	v_cndmask_b32_e64 v209, v208, v209, s[98:99]
	v_fma_f32 v208, -v210, v208, v182
	v_cmp_lt_f32_e64 s[98:99], 0, v208
	s_nop 1
	v_cndmask_b32_e64 v208, v209, v210, s[98:99]
	v_mul_f32_e32 v209, 0x37800000, v208
	v_cndmask_b32_e32 v208, v208, v209, vcc
	v_cmp_class_f32_e32 vcc, v182, v213
	s_nop 1
	v_cndmask_b32_e32 v182, v208, v182, vcc
	v_div_scale_f32 v208, s[98:99], v182, v182, 1.0
	v_rcp_f32_e32 v209, v208
	s_nop 0
	v_fma_f32 v210, -v208, v209, 1.0
	v_fmac_f32_e32 v209, v210, v209
	v_div_scale_f32 v210, vcc, 1.0, v182, 1.0
	v_mul_f32_e32 v211, v210, v209
	v_fma_f32 v212, -v208, v211, v210
	v_fmac_f32_e32 v211, v212, v209
	v_fma_f32 v208, -v208, v211, v210
	v_div_fmas_f32 v208, v208, v209, v211
	v_div_fixup_f32 v182, v208, v182, 1.0
	s_cmp_eq_u32 s8, 4
	s_cbranch_scc1 .Llean_F_sig
; __device__ __forceinline__ unsigned cvt_pk_bf16(float lo, float hi) { unsigned r; asm volatile("v_cvt_pk_bf16_f32 %0, %1, %2" : "=v"(r) : "v"(lo), "v"(hi)); return r; }
; #define GAS __attribute__((address_space(1)))
;     DI void operator()(AccRef acc, const pg8::Unit& u, int wr, int wc, int, int) const {
;     ...
;         for (int m = 0; m < 4; ++m) { const int lrow = u.pm * 256 + ai * 128 + wr * 64 + m * 16 + fr;
;             const float rs = rs8[ai * 4 + m];
;             const f32x4 c0 = rc0[m], c1 = rc1[m], s0 = rs0[m], s1 = rs1[m];
;             EPI_COLS_BEGIN
;                 { const float rsk = (kind == 4) ? rs * -1.4426950408889634f : rs; v0 = v0 * rsk; v1 = v1 * rsk; }
;                 if (kind < 2) {
;                     if (rot) {
;                         f32x4 p0, p1;
; #pragma unroll
;                         for (int e = 0; e < 4; ++e) { p0[e] = lane_xor<16>(v0[e]); p1[e] = lane_xor<16>(v1[e]); }
;                         if (fq == 0) { v0 = v0 * c0 - p0 * s0; v1 = v1 * c1 - p1 * s1; }
;                         else if (fq == 1) { v0 = v0 * c0 + p0 * s0; v1 = v1 * c1 + p1 * s1; }
;                     }
;                     v0 = v0 * qs; v1 = v1 * qs;
;                 } else if (kind == 3) {
;                     f32x2 a = pg8::gelu_pk((f32x2){v0[0], v0[1]}), b = pg8::gelu_pk((f32x2){v0[2], v0[3]}), c = pg8::gelu_pk((f32x2){v1[0], v1[1]}), d = pg8::gelu_pk((f32x2){v1[2], v1[3]});
;                     v0 = (f32x4){a.x, a.y, b.x, b.y}; v1 = (f32x4){c.x, c.y, d.x, d.y};
;                 } else if (kind == 4) {
; #pragma unroll
;                     for (int e = 0; e < 4; ++e) { v0[e] = __builtin_amdgcn_rcpf(1.0f + __builtin_amdgcn_exp2f(v0[e])); v1[e] = __builtin_amdgcn_rcpf(1.0f + __builtin_amdgcn_exp2f(v1[e])); }
;                 }
;                 u32x4 w; w.x = cvt_pk_bf16(v0[0], v0[1]); w.y = cvt_pk_bf16(v0[2], v0[3]); w.z = cvt_pk_bf16(v1[0], v1[1]); w.w = cvt_pk_bf16(v1[2], v1[3]);
;                 *(GAS u32x4*)(dummy ? dummy + lane_ * 8 : Z + (size_t)lrow * ldz + col) = w;
	v_pk_mul_f32 v[188:189], v[188:189], v[168:169] op_sel_hi:[1,0]
	v_pk_mul_f32 v[190:191], v[190:191], v[168:169] op_sel_hi:[1,0]
	v_pk_mul_f32 v[184:185], v[184:185], v[168:169] op_sel_hi:[1,0]
	v_pk_mul_f32 v[186:187], v[186:187], v[168:169] op_sel_hi:[1,0]
	v_cvt_pk_bf16_f32 v216, v188, v189
	v_cvt_pk_bf16_f32 v217, v190, v191
	v_cvt_pk_bf16_f32 v218, v184, v185
	v_cvt_pk_bf16_f32 v219, v186, v187
	global_store_dwordx4 v[146:147], v[216:219], off
	v_pk_mul_f32 v[164:165], v[164:165], v[168:169] op_sel_hi:[1,0]
	v_pk_mul_f32 v[166:167], v[166:167], v[168:169] op_sel_hi:[1,0]
	v_pk_mul_f32 v[160:161], v[160:161], v[168:169] op_sel_hi:[1,0]
	v_pk_mul_f32 v[162:163], v[162:163], v[168:169] op_sel_hi:[1,0]
	v_cvt_pk_bf16_f32 v220, v164, v165
	v_cvt_pk_bf16_f32 v221, v166, v167
	v_cvt_pk_bf16_f32 v222, v160, v161
	v_cvt_pk_bf16_f32 v223, v162, v163
	global_store_dwordx4 v[146:147], v[220:223], off offset:256
	v_lshl_add_u64 v[150:151], v[146:147], 0, s[2:3]
	v_pk_mul_f32 v[156:157], v[156:157], v[170:171] op_sel_hi:[1,0]
	v_pk_mul_f32 v[158:159], v[158:159], v[170:171] op_sel_hi:[1,0]
	v_pk_mul_f32 v[152:153], v[152:153], v[170:171] op_sel_hi:[1,0]
	v_pk_mul_f32 v[154:155], v[154:155], v[170:171] op_sel_hi:[1,0]
	v_cvt_pk_bf16_f32 v224, v156, v157
	v_cvt_pk_bf16_f32 v225, v158, v159
	v_cvt_pk_bf16_f32 v226, v152, v153
	v_cvt_pk_bf16_f32 v227, v154, v155
	global_store_dwordx4 v[150:151], v[224:227], off
	v_pk_mul_f32 v[132:133], v[132:133], v[170:171] op_sel_hi:[1,0]
	v_pk_mul_f32 v[134:135], v[134:135], v[170:171] op_sel_hi:[1,0]
	v_pk_mul_f32 v[128:129], v[128:129], v[170:171] op_sel_hi:[1,0]
	v_pk_mul_f32 v[130:131], v[130:131], v[170:171] op_sel_hi:[1,0]
	v_cvt_pk_bf16_f32 v228, v132, v133
	v_cvt_pk_bf16_f32 v229, v134, v135
	v_cvt_pk_bf16_f32 v230, v128, v129
	v_cvt_pk_bf16_f32 v231, v130, v131
	global_store_dwordx4 v[150:151], v[228:231], off offset:256
	v_lshl_add_u64 v[146:147], v[150:151], 0, s[2:3]
	v_pk_mul_f32 v[124:125], v[124:125], v[172:173] op_sel_hi:[1,0]
	v_pk_mul_f32 v[126:127], v[126:127], v[172:173] op_sel_hi:[1,0]
	v_pk_mul_f32 v[120:121], v[120:121], v[172:173] op_sel_hi:[1,0]
	v_pk_mul_f32 v[122:123], v[122:123], v[172:173] op_sel_hi:[1,0]
	v_cvt_pk_bf16_f32 v216, v124, v125
	v_cvt_pk_bf16_f32 v217, v126, v127
	v_cvt_pk_bf16_f32 v218, v120, v121
	v_cvt_pk_bf16_f32 v219, v122, v123
	global_store_dwordx4 v[146:147], v[216:219], off
	v_pk_mul_f32 v[100:101], v[100:101], v[172:173] op_sel_hi:[1,0]
	v_pk_mul_f32 v[102:103], v[102:103], v[172:173] op_sel_hi:[1,0]
	v_pk_mul_f32 v[96:97], v[96:97], v[172:173] op_sel_hi:[1,0]
	v_pk_mul_f32 v[98:99], v[98:99], v[172:173] op_sel_hi:[1,0]
	v_cvt_pk_bf16_f32 v220, v100, v101
	v_cvt_pk_bf16_f32 v221, v102, v103
	v_cvt_pk_bf16_f32 v222, v96, v97
	v_cvt_pk_bf16_f32 v223, v98, v99
	global_store_dwordx4 v[146:147], v[220:223], off offset:256
	v_lshl_add_u64 v[150:151], v[146:147], 0, s[2:3]
	v_pk_mul_f32 v[92:93], v[92:93], v[174:175] op_sel_hi:[1,0]
	v_pk_mul_f32 v[94:95], v[94:95], v[174:175] op_sel_hi:[1,0]
	v_pk_mul_f32 v[88:89], v[88:89], v[174:175] op_sel_hi:[1,0]
	v_pk_mul_f32 v[90:91], v[90:91], v[174:175] op_sel_hi:[1,0]
	v_cvt_pk_bf16_f32 v224, v92, v93
	v_cvt_pk_bf16_f32 v225, v94, v95
	v_cvt_pk_bf16_f32 v226, v88, v89
	v_cvt_pk_bf16_f32 v227, v90, v91
	global_store_dwordx4 v[150:151], v[224:227], off
	v_pk_mul_f32 v[68:69], v[68:69], v[174:175] op_sel_hi:[1,0]
	v_pk_mul_f32 v[70:71], v[70:71], v[174:175] op_sel_hi:[1,0]
	v_pk_mul_f32 v[64:65], v[64:65], v[174:175] op_sel_hi:[1,0]
	v_pk_mul_f32 v[66:67], v[66:67], v[174:175] op_sel_hi:[1,0]
	v_cvt_pk_bf16_f32 v228, v68, v69
	v_cvt_pk_bf16_f32 v229, v70, v71
	v_cvt_pk_bf16_f32 v230, v64, v65
	v_cvt_pk_bf16_f32 v231, v66, v67
	global_store_dwordx4 v[150:151], v[228:231], off offset:256
	v_lshl_add_u64 v[146:147], v[150:151], 0, s[0:1]
	v_pk_mul_f32 v[60:61], v[60:61], v[176:177] op_sel_hi:[1,0]
	v_pk_mul_f32 v[62:63], v[62:63], v[176:177] op_sel_hi:[1,0]
	v_pk_mul_f32 v[56:57], v[56:57], v[176:177] op_sel_hi:[1,0]
	v_pk_mul_f32 v[58:59], v[58:59], v[176:177] op_sel_hi:[1,0]
	v_cvt_pk_bf16_f32 v216, v60, v61
	v_cvt_pk_bf16_f32 v217, v62, v63
	v_cvt_pk_bf16_f32 v218, v56, v57
	v_cvt_pk_bf16_f32 v219, v58, v59
	global_store_dwordx4 v[146:147], v[216:219], off
	v_pk_mul_f32 v[52:53], v[52:53], v[176:177] op_sel_hi:[1,0]
	v_pk_mul_f32 v[54:55], v[54:55], v[176:177] op_sel_hi:[1,0]
	v_pk_mul_f32 v[48:49], v[48:49], v[176:177] op_sel_hi:[1,0]
	v_pk_mul_f32 v[50:51], v[50:51], v[176:177] op_sel_hi:[1,0]
	v_cvt_pk_bf16_f32 v220, v52, v53
	v_cvt_pk_bf16_f32 v221, v54, v55
	v_cvt_pk_bf16_f32 v222, v48, v49
	v_cvt_pk_bf16_f32 v223, v50, v51
	global_store_dwordx4 v[146:147], v[220:223], off offset:256
	v_lshl_add_u64 v[150:151], v[146:147], 0, s[2:3]
	v_pk_mul_f32 v[44:45], v[44:45], v[178:179] op_sel_hi:[1,0]
	v_pk_mul_f32 v[46:47], v[46:47], v[178:179] op_sel_hi:[1,0]
	v_pk_mul_f32 v[40:41], v[40:41], v[178:179] op_sel_hi:[1,0]
	v_pk_mul_f32 v[42:43], v[42:43], v[178:179] op_sel_hi:[1,0]
	v_cvt_pk_bf16_f32 v224, v44, v45
	v_cvt_pk_bf16_f32 v225, v46, v47
	v_cvt_pk_bf16_f32 v226, v40, v41
	v_cvt_pk_bf16_f32 v227, v42, v43
	global_store_dwordx4 v[150:151], v[224:227], off
	v_pk_mul_f32 v[36:37], v[36:37], v[178:179] op_sel_hi:[1,0]
	v_pk_mul_f32 v[38:39], v[38:39], v[178:179] op_sel_hi:[1,0]
	v_pk_mul_f32 v[32:33], v[32:33], v[178:179] op_sel_hi:[1,0]
	v_pk_mul_f32 v[34:35], v[34:35], v[178:179] op_sel_hi:[1,0]
	v_cvt_pk_bf16_f32 v228, v36, v37
	v_cvt_pk_bf16_f32 v229, v38, v39
	v_cvt_pk_bf16_f32 v230, v32, v33
	v_cvt_pk_bf16_f32 v231, v34, v35
	global_store_dwordx4 v[150:151], v[228:231], off offset:256
	v_lshl_add_u64 v[146:147], v[150:151], 0, s[2:3]
; __device__ __forceinline__ unsigned cvt_pk_bf16(float lo, float hi) { unsigned r; asm volatile("v_cvt_pk_bf16_f32 %0, %1, %2" : "=v"(r) : "v"(lo), "v"(hi)); return r; }
; #define GAS __attribute__((address_space(1)))
;     DI void operator()(AccRef acc, const pg8::Unit& u, int wr, int wc, int, int) const {
;     ...
;                 { const float rsk = (kind == 4) ? rs * -1.4426950408889634f : rs; v0 = v0 * rsk; v1 = v1 * rsk; }
;                 if (kind < 2) {
;                     if (rot) {
;                         f32x4 p0, p1;
; #pragma unroll
;                         for (int e = 0; e < 4; ++e) { p0[e] = lane_xor<16>(v0[e]); p1[e] = lane_xor<16>(v1[e]); }
;                         if (fq == 0) { v0 = v0 * c0 - p0 * s0; v1 = v1 * c1 - p1 * s1; }
;                         else if (fq == 1) { v0 = v0 * c0 + p0 * s0; v1 = v1 * c1 + p1 * s1; }
;                     }
;                     v0 = v0 * qs; v1 = v1 * qs;
;                 } else if (kind == 3) {
;                     f32x2 a = pg8::gelu_pk((f32x2){v0[0], v0[1]}), b = pg8::gelu_pk((f32x2){v0[2], v0[3]}), c = pg8::gelu_pk((f32x2){v1[0], v1[1]}), d = pg8::gelu_pk((f32x2){v1[2], v1[3]});
;                     v0 = (f32x4){a.x, a.y, b.x, b.y}; v1 = (f32x4){c.x, c.y, d.x, d.y};
;                 } else if (kind == 4) {
; #pragma unroll
;                     for (int e = 0; e < 4; ++e) { v0[e] = __builtin_amdgcn_rcpf(1.0f + __builtin_amdgcn_exp2f(v0[e])); v1[e] = __builtin_amdgcn_rcpf(1.0f + __builtin_amdgcn_exp2f(v1[e])); }
;                 }
;                 u32x4 w; w.x = cvt_pk_bf16(v0[0], v0[1]); w.y = cvt_pk_bf16(v0[2], v0[3]); w.z = cvt_pk_bf16(v1[0], v1[1]); w.w = cvt_pk_bf16(v1[2], v1[3]);
;                 *(GAS u32x4*)(dummy ? dummy + lane_ * 8 : Z + (size_t)lrow * ldz + col) = w;
	v_pk_mul_f32 v[28:29], v[28:29], v[180:181] op_sel_hi:[1,0]
	v_pk_mul_f32 v[30:31], v[30:31], v[180:181] op_sel_hi:[1,0]
	v_pk_mul_f32 v[24:25], v[24:25], v[180:181] op_sel_hi:[1,0]
	v_pk_mul_f32 v[26:27], v[26:27], v[180:181] op_sel_hi:[1,0]
	v_cvt_pk_bf16_f32 v216, v28, v29
	v_cvt_pk_bf16_f32 v217, v30, v31
	v_cvt_pk_bf16_f32 v218, v24, v25
	v_cvt_pk_bf16_f32 v219, v26, v27
	global_store_dwordx4 v[146:147], v[216:219], off
	v_pk_mul_f32 v[20:21], v[20:21], v[180:181] op_sel_hi:[1,0]
	v_pk_mul_f32 v[22:23], v[22:23], v[180:181] op_sel_hi:[1,0]
	v_pk_mul_f32 v[16:17], v[16:17], v[180:181] op_sel_hi:[1,0]
	v_pk_mul_f32 v[18:19], v[18:19], v[180:181] op_sel_hi:[1,0]
	v_cvt_pk_bf16_f32 v220, v20, v21
	v_cvt_pk_bf16_f32 v221, v22, v23
	v_cvt_pk_bf16_f32 v222, v16, v17
	v_cvt_pk_bf16_f32 v223, v18, v19
	global_store_dwordx4 v[146:147], v[220:223], off offset:256
	v_lshl_add_u64 v[150:151], v[146:147], 0, s[2:3]
	v_pk_mul_f32 v[12:13], v[12:13], v[182:183] op_sel_hi:[1,0]
	v_pk_mul_f32 v[14:15], v[14:15], v[182:183] op_sel_hi:[1,0]
	v_pk_mul_f32 v[8:9], v[8:9], v[182:183] op_sel_hi:[1,0]
	v_pk_mul_f32 v[10:11], v[10:11], v[182:183] op_sel_hi:[1,0]
	v_cvt_pk_bf16_f32 v224, v12, v13
	v_cvt_pk_bf16_f32 v225, v14, v15
	v_cvt_pk_bf16_f32 v226, v8, v9
	v_cvt_pk_bf16_f32 v227, v10, v11
	global_store_dwordx4 v[150:151], v[224:227], off
	v_pk_mul_f32 v[4:5], v[4:5], v[182:183] op_sel_hi:[1,0]
	v_pk_mul_f32 v[6:7], v[6:7], v[182:183] op_sel_hi:[1,0]
	v_pk_mul_f32 v[0:1], v[0:1], v[182:183] op_sel_hi:[1,0]
	v_pk_mul_f32 v[2:3], v[2:3], v[182:183] op_sel_hi:[1,0]
	v_cvt_pk_bf16_f32 v228, v4, v5
	v_cvt_pk_bf16_f32 v229, v6, v7
	v_cvt_pk_bf16_f32 v230, v0, v1
	v_cvt_pk_bf16_f32 v231, v2, v3
	global_store_dwordx4 v[150:151], v[228:231], off offset:256
	s_branch .Llean_F_exit
.Llean_F_sig:
	v_mul_f32_e32 v168, 0xbfb8aa3b, v168
	v_mul_f32_e32 v170, 0xbfb8aa3b, v170
	v_mul_f32_e32 v172, 0xbfb8aa3b, v172
	v_mul_f32_e32 v174, 0xbfb8aa3b, v174
	v_mul_f32_e32 v176, 0xbfb8aa3b, v176
	v_mul_f32_e32 v178, 0xbfb8aa3b, v178
	v_mul_f32_e32 v180, 0xbfb8aa3b, v180
	v_mul_f32_e32 v182, 0xbfb8aa3b, v182
	v_pk_mul_f32 v[188:189], v[188:189], v[168:169] op_sel_hi:[1,0]
	v_pk_mul_f32 v[190:191], v[190:191], v[168:169] op_sel_hi:[1,0]
	v_pk_mul_f32 v[184:185], v[184:185], v[168:169] op_sel_hi:[1,0]
	v_pk_mul_f32 v[186:187], v[186:187], v[168:169] op_sel_hi:[1,0]
	v_exp_f32_e32 v188, v188
	v_exp_f32_e32 v189, v189
	v_exp_f32_e32 v190, v190
	v_exp_f32_e32 v191, v191
	v_exp_f32_e32 v184, v184
	v_exp_f32_e32 v185, v185
	v_exp_f32_e32 v186, v186
	v_exp_f32_e32 v187, v187
	v_add_f32_e32 v188, 1.0, v188
	v_add_f32_e32 v189, 1.0, v189
	v_add_f32_e32 v190, 1.0, v190
	v_add_f32_e32 v191, 1.0, v191
	v_add_f32_e32 v184, 1.0, v184
	v_add_f32_e32 v185, 1.0, v185
	v_add_f32_e32 v186, 1.0, v186
	v_add_f32_e32 v187, 1.0, v187
	v_rcp_f32_e32 v188, v188
	v_rcp_f32_e32 v189, v189
	v_rcp_f32_e32 v190, v190
	v_rcp_f32_e32 v191, v191
	v_rcp_f32_e32 v184, v184
	v_rcp_f32_e32 v185, v185
	v_rcp_f32_e32 v186, v186
	v_rcp_f32_e32 v187, v187
	s_nop 0
	v_cvt_pk_bf16_f32 v216, v188, v189
	v_cvt_pk_bf16_f32 v217, v190, v191
	v_cvt_pk_bf16_f32 v218, v184, v185
	v_cvt_pk_bf16_f32 v219, v186, v187
	global_store_dwordx4 v[146:147], v[216:219], off
	v_pk_mul_f32 v[164:165], v[164:165], v[168:169] op_sel_hi:[1,0]
	v_pk_mul_f32 v[166:167], v[166:167], v[168:169] op_sel_hi:[1,0]
	v_pk_mul_f32 v[160:161], v[160:161], v[168:169] op_sel_hi:[1,0]
	v_pk_mul_f32 v[162:163], v[162:163], v[168:169] op_sel_hi:[1,0]
	v_exp_f32_e32 v164, v164
	v_exp_f32_e32 v165, v165
	v_exp_f32_e32 v166, v166
	v_exp_f32_e32 v167, v167
	v_exp_f32_e32 v160, v160
	v_exp_f32_e32 v161, v161
	v_exp_f32_e32 v162, v162
	v_exp_f32_e32 v163, v163
	v_add_f32_e32 v164, 1.0, v164
	v_add_f32_e32 v165, 1.0, v165
	v_add_f32_e32 v166, 1.0, v166
	v_add_f32_e32 v167, 1.0, v167
	v_add_f32_e32 v160, 1.0, v160
	v_add_f32_e32 v161, 1.0, v161
	v_add_f32_e32 v162, 1.0, v162
	v_add_f32_e32 v163, 1.0, v163
	v_rcp_f32_e32 v164, v164
	v_rcp_f32_e32 v165, v165
	v_rcp_f32_e32 v166, v166
	v_rcp_f32_e32 v167, v167
	v_rcp_f32_e32 v160, v160
	v_rcp_f32_e32 v161, v161
	v_rcp_f32_e32 v162, v162
	v_rcp_f32_e32 v163, v163
	s_nop 0
	v_cvt_pk_bf16_f32 v220, v164, v165
	v_cvt_pk_bf16_f32 v221, v166, v167
	v_cvt_pk_bf16_f32 v222, v160, v161
	v_cvt_pk_bf16_f32 v223, v162, v163
	global_store_dwordx4 v[146:147], v[220:223], off offset:256
	v_lshl_add_u64 v[150:151], v[146:147], 0, s[2:3]
	v_pk_mul_f32 v[156:157], v[156:157], v[170:171] op_sel_hi:[1,0]
	v_pk_mul_f32 v[158:159], v[158:159], v[170:171] op_sel_hi:[1,0]
	v_pk_mul_f32 v[152:153], v[152:153], v[170:171] op_sel_hi:[1,0]
	v_pk_mul_f32 v[154:155], v[154:155], v[170:171] op_sel_hi:[1,0]
	v_exp_f32_e32 v156, v156
	v_exp_f32_e32 v157, v157
	v_exp_f32_e32 v158, v158
	v_exp_f32_e32 v159, v159
	v_exp_f32_e32 v152, v152
	v_exp_f32_e32 v153, v153
	v_exp_f32_e32 v154, v154
	v_exp_f32_e32 v155, v155
	v_add_f32_e32 v156, 1.0, v156
	v_add_f32_e32 v157, 1.0, v157
	v_add_f32_e32 v158, 1.0, v158
	v_add_f32_e32 v159, 1.0, v159
	v_add_f32_e32 v152, 1.0, v152
	v_add_f32_e32 v153, 1.0, v153
	v_add_f32_e32 v154, 1.0, v154
	v_add_f32_e32 v155, 1.0, v155
	v_rcp_f32_e32 v156, v156
	v_rcp_f32_e32 v157, v157
	v_rcp_f32_e32 v158, v158
	v_rcp_f32_e32 v159, v159
	v_rcp_f32_e32 v152, v152
	v_rcp_f32_e32 v153, v153
	v_rcp_f32_e32 v154, v154
	v_rcp_f32_e32 v155, v155
	s_nop 0
	v_cvt_pk_bf16_f32 v224, v156, v157
	v_cvt_pk_bf16_f32 v225, v158, v159
	v_cvt_pk_bf16_f32 v226, v152, v153
	v_cvt_pk_bf16_f32 v227, v154, v155
	global_store_dwordx4 v[150:151], v[224:227], off
	v_pk_mul_f32 v[132:133], v[132:133], v[170:171] op_sel_hi:[1,0]
; __device__ __forceinline__ unsigned cvt_pk_bf16(float lo, float hi) { unsigned r; asm volatile("v_cvt_pk_bf16_f32 %0, %1, %2" : "=v"(r) : "v"(lo), "v"(hi)); return r; }
; #define GAS __attribute__((address_space(1)))
;     DI void operator()(AccRef acc, const pg8::Unit& u, int wr, int wc, int, int) const {
;     ...
;                 } else if (kind == 4) {
; #pragma unroll
;                     for (int e = 0; e < 4; ++e) { v0[e] = __builtin_amdgcn_rcpf(1.0f + __builtin_amdgcn_exp2f(v0[e])); v1[e] = __builtin_amdgcn_rcpf(1.0f + __builtin_amdgcn_exp2f(v1[e])); }
;                 }
;                 u32x4 w; w.x = cvt_pk_bf16(v0[0], v0[1]); w.y = cvt_pk_bf16(v0[2], v0[3]); w.z = cvt_pk_bf16(v1[0], v1[1]); w.w = cvt_pk_bf16(v1[2], v1[3]);
;                 *(GAS u32x4*)(dummy ? dummy + lane_ * 8 : Z + (size_t)lrow * ldz + col) = w;
	v_pk_mul_f32 v[134:135], v[134:135], v[170:171] op_sel_hi:[1,0]
	v_pk_mul_f32 v[128:129], v[128:129], v[170:171] op_sel_hi:[1,0]
	v_pk_mul_f32 v[130:131], v[130:131], v[170:171] op_sel_hi:[1,0]
	v_exp_f32_e32 v132, v132
	v_exp_f32_e32 v133, v133
	v_exp_f32_e32 v134, v134
	v_exp_f32_e32 v135, v135
	v_exp_f32_e32 v128, v128
	v_exp_f32_e32 v129, v129
	v_exp_f32_e32 v130, v130
	v_exp_f32_e32 v131, v131
	v_add_f32_e32 v132, 1.0, v132
	v_add_f32_e32 v133, 1.0, v133
	v_add_f32_e32 v134, 1.0, v134
	v_add_f32_e32 v135, 1.0, v135
	v_add_f32_e32 v128, 1.0, v128
	v_add_f32_e32 v129, 1.0, v129
	v_add_f32_e32 v130, 1.0, v130
	v_add_f32_e32 v131, 1.0, v131
	v_rcp_f32_e32 v132, v132
	v_rcp_f32_e32 v133, v133
	v_rcp_f32_e32 v134, v134
	v_rcp_f32_e32 v135, v135
	v_rcp_f32_e32 v128, v128
	v_rcp_f32_e32 v129, v129
	v_rcp_f32_e32 v130, v130
	v_rcp_f32_e32 v131, v131
	s_nop 0
	v_cvt_pk_bf16_f32 v228, v132, v133
	v_cvt_pk_bf16_f32 v229, v134, v135
	v_cvt_pk_bf16_f32 v230, v128, v129
	v_cvt_pk_bf16_f32 v231, v130, v131
	global_store_dwordx4 v[150:151], v[228:231], off offset:256
	v_lshl_add_u64 v[146:147], v[150:151], 0, s[2:3]
	v_pk_mul_f32 v[124:125], v[124:125], v[172:173] op_sel_hi:[1,0]
	v_pk_mul_f32 v[126:127], v[126:127], v[172:173] op_sel_hi:[1,0]
	v_pk_mul_f32 v[120:121], v[120:121], v[172:173] op_sel_hi:[1,0]
	v_pk_mul_f32 v[122:123], v[122:123], v[172:173] op_sel_hi:[1,0]
	v_exp_f32_e32 v124, v124
	v_exp_f32_e32 v125, v125
	v_exp_f32_e32 v126, v126
	v_exp_f32_e32 v127, v127
	v_exp_f32_e32 v120, v120
	v_exp_f32_e32 v121, v121
	v_exp_f32_e32 v122, v122
	v_exp_f32_e32 v123, v123
	v_add_f32_e32 v124, 1.0, v124
	v_add_f32_e32 v125, 1.0, v125
	v_add_f32_e32 v126, 1.0, v126
	v_add_f32_e32 v127, 1.0, v127
	v_add_f32_e32 v120, 1.0, v120
	v_add_f32_e32 v121, 1.0, v121
	v_add_f32_e32 v122, 1.0, v122
	v_add_f32_e32 v123, 1.0, v123
	v_rcp_f32_e32 v124, v124
	v_rcp_f32_e32 v125, v125
	v_rcp_f32_e32 v126, v126
	v_rcp_f32_e32 v127, v127
	v_rcp_f32_e32 v120, v120
	v_rcp_f32_e32 v121, v121
	v_rcp_f32_e32 v122, v122
	v_rcp_f32_e32 v123, v123
	s_nop 0
	v_cvt_pk_bf16_f32 v216, v124, v125
	v_cvt_pk_bf16_f32 v217, v126, v127
	v_cvt_pk_bf16_f32 v218, v120, v121
	v_cvt_pk_bf16_f32 v219, v122, v123
	global_store_dwordx4 v[146:147], v[216:219], off
	v_pk_mul_f32 v[100:101], v[100:101], v[172:173] op_sel_hi:[1,0]
	v_pk_mul_f32 v[102:103], v[102:103], v[172:173] op_sel_hi:[1,0]
	v_pk_mul_f32 v[96:97], v[96:97], v[172:173] op_sel_hi:[1,0]
	v_pk_mul_f32 v[98:99], v[98:99], v[172:173] op_sel_hi:[1,0]
	v_exp_f32_e32 v100, v100
	v_exp_f32_e32 v101, v101
	v_exp_f32_e32 v102, v102
	v_exp_f32_e32 v103, v103
	v_exp_f32_e32 v96, v96
	v_exp_f32_e32 v97, v97
	v_exp_f32_e32 v98, v98
	v_exp_f32_e32 v99, v99
	v_add_f32_e32 v100, 1.0, v100
	v_add_f32_e32 v101, 1.0, v101
	v_add_f32_e32 v102, 1.0, v102
	v_add_f32_e32 v103, 1.0, v103
	v_add_f32_e32 v96, 1.0, v96
	v_add_f32_e32 v97, 1.0, v97
	v_add_f32_e32 v98, 1.0, v98
	v_add_f32_e32 v99, 1.0, v99
	v_rcp_f32_e32 v100, v100
	v_rcp_f32_e32 v101, v101
	v_rcp_f32_e32 v102, v102
	v_rcp_f32_e32 v103, v103
	v_rcp_f32_e32 v96, v96
	v_rcp_f32_e32 v97, v97
	v_rcp_f32_e32 v98, v98
	v_rcp_f32_e32 v99, v99
	s_nop 0
	v_cvt_pk_bf16_f32 v220, v100, v101
	v_cvt_pk_bf16_f32 v221, v102, v103
	v_cvt_pk_bf16_f32 v222, v96, v97
	v_cvt_pk_bf16_f32 v223, v98, v99
	global_store_dwordx4 v[146:147], v[220:223], off offset:256
	v_lshl_add_u64 v[150:151], v[146:147], 0, s[2:3]
	v_pk_mul_f32 v[92:93], v[92:93], v[174:175] op_sel_hi:[1,0]
	v_pk_mul_f32 v[94:95], v[94:95], v[174:175] op_sel_hi:[1,0]
	v_pk_mul_f32 v[88:89], v[88:89], v[174:175] op_sel_hi:[1,0]
	v_pk_mul_f32 v[90:91], v[90:91], v[174:175] op_sel_hi:[1,0]
	v_exp_f32_e32 v92, v92
	v_exp_f32_e32 v93, v93
	v_exp_f32_e32 v94, v94
	v_exp_f32_e32 v95, v95
	v_exp_f32_e32 v88, v88
	v_exp_f32_e32 v89, v89
	v_exp_f32_e32 v90, v90
	v_exp_f32_e32 v91, v91
	v_add_f32_e32 v92, 1.0, v92
	v_add_f32_e32 v93, 1.0, v93
	v_add_f32_e32 v94, 1.0, v94
	v_add_f32_e32 v95, 1.0, v95
	v_add_f32_e32 v88, 1.0, v88
	v_add_f32_e32 v89, 1.0, v89
	v_add_f32_e32 v90, 1.0, v90
	v_add_f32_e32 v91, 1.0, v91
	v_rcp_f32_e32 v92, v92
	v_rcp_f32_e32 v93, v93
	v_rcp_f32_e32 v94, v94
	v_rcp_f32_e32 v95, v95
	v_rcp_f32_e32 v88, v88
	v_rcp_f32_e32 v89, v89
	v_rcp_f32_e32 v90, v90
	v_rcp_f32_e32 v91, v91
	s_nop 0
	v_cvt_pk_bf16_f32 v224, v92, v93
	v_cvt_pk_bf16_f32 v225, v94, v95
	v_cvt_pk_bf16_f32 v226, v88, v89
	v_cvt_pk_bf16_f32 v227, v90, v91
	global_store_dwordx4 v[150:151], v[224:227], off
	v_pk_mul_f32 v[68:69], v[68:69], v[174:175] op_sel_hi:[1,0]
	v_pk_mul_f32 v[70:71], v[70:71], v[174:175] op_sel_hi:[1,0]
	v_pk_mul_f32 v[64:65], v[64:65], v[174:175] op_sel_hi:[1,0]
	v_pk_mul_f32 v[66:67], v[66:67], v[174:175] op_sel_hi:[1,0]
	v_exp_f32_e32 v68, v68
	v_exp_f32_e32 v69, v69
	v_exp_f32_e32 v70, v70
	v_exp_f32_e32 v71, v71
	v_exp_f32_e32 v64, v64
	v_exp_f32_e32 v65, v65
	v_exp_f32_e32 v66, v66
	v_exp_f32_e32 v67, v67
	v_add_f32_e32 v68, 1.0, v68
	v_add_f32_e32 v69, 1.0, v69
	v_add_f32_e32 v70, 1.0, v70
	v_add_f32_e32 v71, 1.0, v71
	v_add_f32_e32 v64, 1.0, v64
	v_add_f32_e32 v65, 1.0, v65
	v_add_f32_e32 v66, 1.0, v66
	v_add_f32_e32 v67, 1.0, v67
	v_rcp_f32_e32 v68, v68
	v_rcp_f32_e32 v69, v69
	v_rcp_f32_e32 v70, v70
	v_rcp_f32_e32 v71, v71
	v_rcp_f32_e32 v64, v64
	v_rcp_f32_e32 v65, v65
	v_rcp_f32_e32 v66, v66
	v_rcp_f32_e32 v67, v67
	s_nop 0
	v_cvt_pk_bf16_f32 v228, v68, v69
	v_cvt_pk_bf16_f32 v229, v70, v71
	v_cvt_pk_bf16_f32 v230, v64, v65
	v_cvt_pk_bf16_f32 v231, v66, v67
	global_store_dwordx4 v[150:151], v[228:231], off offset:256
	v_lshl_add_u64 v[146:147], v[150:151], 0, s[0:1]
	v_pk_mul_f32 v[60:61], v[60:61], v[176:177] op_sel_hi:[1,0]
; __device__ __forceinline__ unsigned cvt_pk_bf16(float lo, float hi) { unsigned r; asm volatile("v_cvt_pk_bf16_f32 %0, %1, %2" : "=v"(r) : "v"(lo), "v"(hi)); return r; }
; #define GAS __attribute__((address_space(1)))
;     DI void operator()(AccRef acc, const pg8::Unit& u, int wr, int wc, int, int) const {
;     ...
;                 } else if (kind == 4) {
; #pragma unroll
;                     for (int e = 0; e < 4; ++e) { v0[e] = __builtin_amdgcn_rcpf(1.0f + __builtin_amdgcn_exp2f(v0[e])); v1[e] = __builtin_amdgcn_rcpf(1.0f + __builtin_amdgcn_exp2f(v1[e])); }
;                 }
;                 u32x4 w; w.x = cvt_pk_bf16(v0[0], v0[1]); w.y = cvt_pk_bf16(v0[2], v0[3]); w.z = cvt_pk_bf16(v1[0], v1[1]); w.w = cvt_pk_bf16(v1[2], v1[3]);
;                 *(GAS u32x4*)(dummy ? dummy + lane_ * 8 : Z + (size_t)lrow * ldz + col) = w;
	v_pk_mul_f32 v[62:63], v[62:63], v[176:177] op_sel_hi:[1,0]
	v_pk_mul_f32 v[56:57], v[56:57], v[176:177] op_sel_hi:[1,0]
	v_pk_mul_f32 v[58:59], v[58:59], v[176:177] op_sel_hi:[1,0]
	v_exp_f32_e32 v60, v60
	v_exp_f32_e32 v61, v61
	v_exp_f32_e32 v62, v62
	v_exp_f32_e32 v63, v63
	v_exp_f32_e32 v56, v56
	v_exp_f32_e32 v57, v57
	v_exp_f32_e32 v58, v58
	v_exp_f32_e32 v59, v59
	v_add_f32_e32 v60, 1.0, v60
	v_add_f32_e32 v61, 1.0, v61
	v_add_f32_e32 v62, 1.0, v62
	v_add_f32_e32 v63, 1.0, v63
	v_add_f32_e32 v56, 1.0, v56
	v_add_f32_e32 v57, 1.0, v57
	v_add_f32_e32 v58, 1.0, v58
	v_add_f32_e32 v59, 1.0, v59
	v_rcp_f32_e32 v60, v60
	v_rcp_f32_e32 v61, v61
	v_rcp_f32_e32 v62, v62
	v_rcp_f32_e32 v63, v63
	v_rcp_f32_e32 v56, v56
	v_rcp_f32_e32 v57, v57
	v_rcp_f32_e32 v58, v58
	v_rcp_f32_e32 v59, v59
	s_nop 0
	v_cvt_pk_bf16_f32 v216, v60, v61
	v_cvt_pk_bf16_f32 v217, v62, v63
	v_cvt_pk_bf16_f32 v218, v56, v57
	v_cvt_pk_bf16_f32 v219, v58, v59
	global_store_dwordx4 v[146:147], v[216:219], off
	v_pk_mul_f32 v[52:53], v[52:53], v[176:177] op_sel_hi:[1,0]
	v_pk_mul_f32 v[54:55], v[54:55], v[176:177] op_sel_hi:[1,0]
	v_pk_mul_f32 v[48:49], v[48:49], v[176:177] op_sel_hi:[1,0]
	v_pk_mul_f32 v[50:51], v[50:51], v[176:177] op_sel_hi:[1,0]
	v_exp_f32_e32 v52, v52
	v_exp_f32_e32 v53, v53
	v_exp_f32_e32 v54, v54
	v_exp_f32_e32 v55, v55
	v_exp_f32_e32 v48, v48
	v_exp_f32_e32 v49, v49
	v_exp_f32_e32 v50, v50
	v_exp_f32_e32 v51, v51
	v_add_f32_e32 v52, 1.0, v52
	v_add_f32_e32 v53, 1.0, v53
	v_add_f32_e32 v54, 1.0, v54
	v_add_f32_e32 v55, 1.0, v55
	v_add_f32_e32 v48, 1.0, v48
	v_add_f32_e32 v49, 1.0, v49
	v_add_f32_e32 v50, 1.0, v50
	v_add_f32_e32 v51, 1.0, v51
	v_rcp_f32_e32 v52, v52
	v_rcp_f32_e32 v53, v53
	v_rcp_f32_e32 v54, v54
	v_rcp_f32_e32 v55, v55
	v_rcp_f32_e32 v48, v48
	v_rcp_f32_e32 v49, v49
	v_rcp_f32_e32 v50, v50
	v_rcp_f32_e32 v51, v51
	s_nop 0
	v_cvt_pk_bf16_f32 v220, v52, v53
	v_cvt_pk_bf16_f32 v221, v54, v55
	v_cvt_pk_bf16_f32 v222, v48, v49
	v_cvt_pk_bf16_f32 v223, v50, v51
	global_store_dwordx4 v[146:147], v[220:223], off offset:256
	v_lshl_add_u64 v[150:151], v[146:147], 0, s[2:3]
	v_pk_mul_f32 v[44:45], v[44:45], v[178:179] op_sel_hi:[1,0]
	v_pk_mul_f32 v[46:47], v[46:47], v[178:179] op_sel_hi:[1,0]
	v_pk_mul_f32 v[40:41], v[40:41], v[178:179] op_sel_hi:[1,0]
	v_pk_mul_f32 v[42:43], v[42:43], v[178:179] op_sel_hi:[1,0]
	v_exp_f32_e32 v44, v44
	v_exp_f32_e32 v45, v45
	v_exp_f32_e32 v46, v46
	v_exp_f32_e32 v47, v47
	v_exp_f32_e32 v40, v40
	v_exp_f32_e32 v41, v41
	v_exp_f32_e32 v42, v42
	v_exp_f32_e32 v43, v43
	v_add_f32_e32 v44, 1.0, v44
	v_add_f32_e32 v45, 1.0, v45
	v_add_f32_e32 v46, 1.0, v46
	v_add_f32_e32 v47, 1.0, v47
	v_add_f32_e32 v40, 1.0, v40
	v_add_f32_e32 v41, 1.0, v41
	v_add_f32_e32 v42, 1.0, v42
	v_add_f32_e32 v43, 1.0, v43
	v_rcp_f32_e32 v44, v44
	v_rcp_f32_e32 v45, v45
	v_rcp_f32_e32 v46, v46
	v_rcp_f32_e32 v47, v47
	v_rcp_f32_e32 v40, v40
	v_rcp_f32_e32 v41, v41
	v_rcp_f32_e32 v42, v42
	v_rcp_f32_e32 v43, v43
	s_nop 0
	v_cvt_pk_bf16_f32 v224, v44, v45
	v_cvt_pk_bf16_f32 v225, v46, v47
	v_cvt_pk_bf16_f32 v226, v40, v41
	v_cvt_pk_bf16_f32 v227, v42, v43
	global_store_dwordx4 v[150:151], v[224:227], off
	v_pk_mul_f32 v[36:37], v[36:37], v[178:179] op_sel_hi:[1,0]
	v_pk_mul_f32 v[38:39], v[38:39], v[178:179] op_sel_hi:[1,0]
	v_pk_mul_f32 v[32:33], v[32:33], v[178:179] op_sel_hi:[1,0]
	v_pk_mul_f32 v[34:35], v[34:35], v[178:179] op_sel_hi:[1,0]
	v_exp_f32_e32 v36, v36
	v_exp_f32_e32 v37, v37
	v_exp_f32_e32 v38, v38
	v_exp_f32_e32 v39, v39
	v_exp_f32_e32 v32, v32
	v_exp_f32_e32 v33, v33
	v_exp_f32_e32 v34, v34
	v_exp_f32_e32 v35, v35
	v_add_f32_e32 v36, 1.0, v36
	v_add_f32_e32 v37, 1.0, v37
	v_add_f32_e32 v38, 1.0, v38
	v_add_f32_e32 v39, 1.0, v39
	v_add_f32_e32 v32, 1.0, v32
	v_add_f32_e32 v33, 1.0, v33
	v_add_f32_e32 v34, 1.0, v34
	v_add_f32_e32 v35, 1.0, v35
	v_rcp_f32_e32 v36, v36
	v_rcp_f32_e32 v37, v37
	v_rcp_f32_e32 v38, v38
	v_rcp_f32_e32 v39, v39
	v_rcp_f32_e32 v32, v32
	v_rcp_f32_e32 v33, v33
	v_rcp_f32_e32 v34, v34
	v_rcp_f32_e32 v35, v35
	s_nop 0
	v_cvt_pk_bf16_f32 v228, v36, v37
	v_cvt_pk_bf16_f32 v229, v38, v39
	v_cvt_pk_bf16_f32 v230, v32, v33
	v_cvt_pk_bf16_f32 v231, v34, v35
	global_store_dwordx4 v[150:151], v[228:231], off offset:256
	v_lshl_add_u64 v[146:147], v[150:151], 0, s[2:3]
	v_pk_mul_f32 v[28:29], v[28:29], v[180:181] op_sel_hi:[1,0]
; __device__ __forceinline__ unsigned cvt_pk_bf16(float lo, float hi) { unsigned r; asm volatile("v_cvt_pk_bf16_f32 %0, %1, %2" : "=v"(r) : "v"(lo), "v"(hi)); return r; }
; #define PG8_BAR __builtin_amdgcn_s_barrier()
; #define GAS __attribute__((address_space(1)))
; template <class Epi, class Sched, bool ALIGN_EPI = false, bool SP2 = false>
; __device__ __forceinline__ void gemm_phase(PG8_LAS unsigned char* lds, const Gemm g, const Sched& S, const Epi& E) {
;     ...
;         if constexpr (ALIGN_EPI) { if (wr == 0) PG8_BAR; }
;         if constexpr (!Epi::AFTER_DRAIN) { E(acc, cur, wr, wc, fr, fq); S.done(cur); }
;         if (!has_next) break;
; #pragma unroll
;         for (int a = 0; a < 2; ++a)
; #pragma unroll
;             for (int b = 0; b < 2; ++b)
; #pragma unroll
;                 for (int m = 0; m < 4; ++m)
; #pragma unroll
;                     for (int n = 0; n < 2; ++n) acc[a][b][m][n] = (f32x4){0.f, 0.f, 0.f, 0.f};
;         cur = nxt; cA = nA; cB = nB; ++ui;
;         if constexpr (ALIGN_EPI) { if (wr == 1) PG8_BAR; }
;     DI void operator()(AccRef acc, const pg8::Unit& u, int wr, int wc, int, int) const {
;     ...
;                 } else if (kind == 4) {
; #pragma unroll
;                     for (int e = 0; e < 4; ++e) { v0[e] = __builtin_amdgcn_rcpf(1.0f + __builtin_amdgcn_exp2f(v0[e])); v1[e] = __builtin_amdgcn_rcpf(1.0f + __builtin_amdgcn_exp2f(v1[e])); }
;                 }
;                 u32x4 w; w.x = cvt_pk_bf16(v0[0], v0[1]); w.y = cvt_pk_bf16(v0[2], v0[3]); w.z = cvt_pk_bf16(v1[0], v1[1]); w.w = cvt_pk_bf16(v1[2], v1[3]);
;                 *(GAS u32x4*)(dummy ? dummy + lane_ * 8 : Z + (size_t)lrow * ldz + col) = w;
	v_pk_mul_f32 v[30:31], v[30:31], v[180:181] op_sel_hi:[1,0]
	v_pk_mul_f32 v[24:25], v[24:25], v[180:181] op_sel_hi:[1,0]
	v_pk_mul_f32 v[26:27], v[26:27], v[180:181] op_sel_hi:[1,0]
	v_exp_f32_e32 v28, v28
	v_exp_f32_e32 v29, v29
	v_exp_f32_e32 v30, v30
	v_exp_f32_e32 v31, v31
	v_exp_f32_e32 v24, v24
	v_exp_f32_e32 v25, v25
	v_exp_f32_e32 v26, v26
	v_exp_f32_e32 v27, v27
	v_add_f32_e32 v28, 1.0, v28
	v_add_f32_e32 v29, 1.0, v29
	v_add_f32_e32 v30, 1.0, v30
	v_add_f32_e32 v31, 1.0, v31
	v_add_f32_e32 v24, 1.0, v24
	v_add_f32_e32 v25, 1.0, v25
	v_add_f32_e32 v26, 1.0, v26
	v_add_f32_e32 v27, 1.0, v27
	v_rcp_f32_e32 v28, v28
	v_rcp_f32_e32 v29, v29
	v_rcp_f32_e32 v30, v30
	v_rcp_f32_e32 v31, v31
	v_rcp_f32_e32 v24, v24
	v_rcp_f32_e32 v25, v25
	v_rcp_f32_e32 v26, v26
	v_rcp_f32_e32 v27, v27
	s_nop 0
	v_cvt_pk_bf16_f32 v216, v28, v29
	v_cvt_pk_bf16_f32 v217, v30, v31
	v_cvt_pk_bf16_f32 v218, v24, v25
	v_cvt_pk_bf16_f32 v219, v26, v27
	global_store_dwordx4 v[146:147], v[216:219], off
	v_pk_mul_f32 v[20:21], v[20:21], v[180:181] op_sel_hi:[1,0]
	v_pk_mul_f32 v[22:23], v[22:23], v[180:181] op_sel_hi:[1,0]
	v_pk_mul_f32 v[16:17], v[16:17], v[180:181] op_sel_hi:[1,0]
	v_pk_mul_f32 v[18:19], v[18:19], v[180:181] op_sel_hi:[1,0]
	v_exp_f32_e32 v20, v20
	v_exp_f32_e32 v21, v21
	v_exp_f32_e32 v22, v22
	v_exp_f32_e32 v23, v23
	v_exp_f32_e32 v16, v16
	v_exp_f32_e32 v17, v17
	v_exp_f32_e32 v18, v18
	v_exp_f32_e32 v19, v19
	v_add_f32_e32 v20, 1.0, v20
	v_add_f32_e32 v21, 1.0, v21
	v_add_f32_e32 v22, 1.0, v22
	v_add_f32_e32 v23, 1.0, v23
	v_add_f32_e32 v16, 1.0, v16
	v_add_f32_e32 v17, 1.0, v17
	v_add_f32_e32 v18, 1.0, v18
	v_add_f32_e32 v19, 1.0, v19
	v_rcp_f32_e32 v20, v20
	v_rcp_f32_e32 v21, v21
	v_rcp_f32_e32 v22, v22
	v_rcp_f32_e32 v23, v23
	v_rcp_f32_e32 v16, v16
	v_rcp_f32_e32 v17, v17
	v_rcp_f32_e32 v18, v18
	v_rcp_f32_e32 v19, v19
	s_nop 0
	v_cvt_pk_bf16_f32 v220, v20, v21
	v_cvt_pk_bf16_f32 v221, v22, v23
	v_cvt_pk_bf16_f32 v222, v16, v17
	v_cvt_pk_bf16_f32 v223, v18, v19
	global_store_dwordx4 v[146:147], v[220:223], off offset:256
	v_lshl_add_u64 v[150:151], v[146:147], 0, s[2:3]
	v_pk_mul_f32 v[12:13], v[12:13], v[182:183] op_sel_hi:[1,0]
	v_pk_mul_f32 v[14:15], v[14:15], v[182:183] op_sel_hi:[1,0]
	v_pk_mul_f32 v[8:9], v[8:9], v[182:183] op_sel_hi:[1,0]
	v_pk_mul_f32 v[10:11], v[10:11], v[182:183] op_sel_hi:[1,0]
	v_exp_f32_e32 v12, v12
	v_exp_f32_e32 v13, v13
	v_exp_f32_e32 v14, v14
	v_exp_f32_e32 v15, v15
	v_exp_f32_e32 v8, v8
	v_exp_f32_e32 v9, v9
	v_exp_f32_e32 v10, v10
	v_exp_f32_e32 v11, v11
	v_add_f32_e32 v12, 1.0, v12
	v_add_f32_e32 v13, 1.0, v13
	v_add_f32_e32 v14, 1.0, v14
	v_add_f32_e32 v15, 1.0, v15
	v_add_f32_e32 v8, 1.0, v8
	v_add_f32_e32 v9, 1.0, v9
	v_add_f32_e32 v10, 1.0, v10
	v_add_f32_e32 v11, 1.0, v11
	v_rcp_f32_e32 v12, v12
	v_rcp_f32_e32 v13, v13
	v_rcp_f32_e32 v14, v14
	v_rcp_f32_e32 v15, v15
	v_rcp_f32_e32 v8, v8
	v_rcp_f32_e32 v9, v9
	v_rcp_f32_e32 v10, v10
	v_rcp_f32_e32 v11, v11
	s_nop 0
	v_cvt_pk_bf16_f32 v224, v12, v13
	v_cvt_pk_bf16_f32 v225, v14, v15
	v_cvt_pk_bf16_f32 v226, v8, v9
	v_cvt_pk_bf16_f32 v227, v10, v11
	global_store_dwordx4 v[150:151], v[224:227], off
	v_pk_mul_f32 v[4:5], v[4:5], v[182:183] op_sel_hi:[1,0]
	v_pk_mul_f32 v[6:7], v[6:7], v[182:183] op_sel_hi:[1,0]
	v_pk_mul_f32 v[0:1], v[0:1], v[182:183] op_sel_hi:[1,0]
	v_pk_mul_f32 v[2:3], v[2:3], v[182:183] op_sel_hi:[1,0]
	v_exp_f32_e32 v4, v4
	v_exp_f32_e32 v5, v5
	v_exp_f32_e32 v6, v6
	v_exp_f32_e32 v7, v7
	v_exp_f32_e32 v0, v0
	v_exp_f32_e32 v1, v1
	v_exp_f32_e32 v2, v2
	v_exp_f32_e32 v3, v3
	v_add_f32_e32 v4, 1.0, v4
	v_add_f32_e32 v5, 1.0, v5
	v_add_f32_e32 v6, 1.0, v6
	v_add_f32_e32 v7, 1.0, v7
	v_add_f32_e32 v0, 1.0, v0
	v_add_f32_e32 v1, 1.0, v1
	v_add_f32_e32 v2, 1.0, v2
	v_add_f32_e32 v3, 1.0, v3
	v_rcp_f32_e32 v4, v4
	v_rcp_f32_e32 v5, v5
	v_rcp_f32_e32 v6, v6
	v_rcp_f32_e32 v7, v7
	v_rcp_f32_e32 v0, v0
	v_rcp_f32_e32 v1, v1
	v_rcp_f32_e32 v2, v2
	v_rcp_f32_e32 v3, v3
	s_nop 0
	v_cvt_pk_bf16_f32 v228, v4, v5
	v_cvt_pk_bf16_f32 v229, v6, v7
	v_cvt_pk_bf16_f32 v230, v0, v1
	v_cvt_pk_bf16_f32 v231, v2, v3
	global_store_dwordx4 v[150:151], v[228:231], off offset:256
.Llean_F_exit:
	s_andn2_b64 vcc, exec, s[4:5]
	s_mov_b64 s[0:1], -1
	s_cbranch_vccnz .LBB0_813
	s_andn2_b64 vcc, exec, s[86:87]
	s_cbranch_vccnz .LBB0_812
	s_barrier
	s_branch .LBB0_812

; template <class Epi, class Sched, bool ALIGN_EPI = false, bool SP2 = false>
; __device__ __forceinline__ void gemm_phase(PG8_LAS unsigned char* lds, const Gemm g, const Sched& S, const Epi& E) {
;     ...
;         const bool has_next = S.next(ui + 1, nxt);
;         const char* nA = has_next ? (const char*)g.A + (size_t)nxt.pm * tstepA : cA; const char* nB = has_next ? (const char*)g.Bt + (size_t)nxt.pn * tstepB : cB;
;     ...
; #pragma unroll
;         for (int a = 0; a < 2; ++a)
; #pragma unroll
;             for (int b = 0; b < 2; ++b)
; #pragma unroll
;                 for (int m = 0; m < 4; ++m)
; #pragma unroll
;                     for (int n = 0; n < 2; ++n) acc[a][b][m][n] = (f32x4){0.f, 0.f, 0.f, 0.f};
;         cur = nxt; cA = nA; cB = nB; ++ui;
.LBB0_816:
	s_ashr_i32 s91, s90, 31
	s_lshl_b64 s[2:3], s[90:91], 19
	s_add_u32 s82, s24, s2
	s_addc_u32 s83, s25, s3
	s_and_b64 s[2:3], s[4:5], exec
	s_cselect_b32 s7, s83, s9
	s_cselect_b32 s12, s82, s8
	s_ashr_i32 s89, s88, 31
	s_lshl_b64 s[2:3], s[88:89], 19
	s_add_u32 s92, s34, s2
	s_addc_u32 s93, s80, s3
	s_and_b64 s[2:3], s[4:5], exec
	s_cselect_b32 s13, s93, s1
	s_cselect_b32 s15, s92, s0
	s_add_u32 s16, s0, 0x100
	s_addc_u32 s17, s1, 0
	s_add_u32 s0, s8, 0x40080
	v_mov_b32_e32 v0, 0
	s_addc_u32 s1, s9, 0
	s_mov_b32 s78, -2
	v_mov_b32_e32 v1, v0
	v_mov_b32_e32 v2, v0
	v_mov_b32_e32 v3, v0
	v_mov_b32_e32 v4, v0
	v_mov_b32_e32 v5, v0
	v_mov_b32_e32 v6, v0
	v_mov_b32_e32 v7, v0
	v_mov_b32_e32 v16, v0
	v_mov_b32_e32 v17, v0
	v_mov_b32_e32 v18, v0
	v_mov_b32_e32 v19, v0
	v_mov_b32_e32 v20, v0
	v_mov_b32_e32 v21, v0
	v_mov_b32_e32 v22, v0
	v_mov_b32_e32 v23, v0
	v_mov_b32_e32 v32, v0
	v_mov_b32_e32 v33, v0
	v_mov_b32_e32 v34, v0
	v_mov_b32_e32 v35, v0
	v_mov_b32_e32 v36, v0
	v_mov_b32_e32 v37, v0
	v_mov_b32_e32 v38, v0
	v_mov_b32_e32 v39, v0
	v_mov_b32_e32 v48, v0
	v_mov_b32_e32 v49, v0
	v_mov_b32_e32 v50, v0
	v_mov_b32_e32 v51, v0
	v_mov_b32_e32 v52, v0
	v_mov_b32_e32 v53, v0
	v_mov_b32_e32 v54, v0
	v_mov_b32_e32 v55, v0
	v_mov_b32_e32 v8, v0
	v_mov_b32_e32 v9, v0
	v_mov_b32_e32 v10, v0
	v_mov_b32_e32 v11, v0
	v_mov_b32_e32 v12, v0
	v_mov_b32_e32 v13, v0
	v_mov_b32_e32 v14, v0
	v_mov_b32_e32 v15, v0
	v_mov_b32_e32 v24, v0
	v_mov_b32_e32 v25, v0
	v_mov_b32_e32 v26, v0
	v_mov_b32_e32 v27, v0
	v_mov_b32_e32 v28, v0
	v_mov_b32_e32 v29, v0
	v_mov_b32_e32 v30, v0
	v_mov_b32_e32 v31, v0
	v_mov_b32_e32 v40, v0
	v_mov_b32_e32 v41, v0
	v_mov_b32_e32 v42, v0
	v_mov_b32_e32 v43, v0
	v_mov_b32_e32 v44, v0
	v_mov_b32_e32 v45, v0
	v_mov_b32_e32 v46, v0
	v_mov_b32_e32 v47, v0
	v_mov_b32_e32 v56, v0
	v_mov_b32_e32 v57, v0
	v_mov_b32_e32 v58, v0
	v_mov_b32_e32 v59, v0
	v_mov_b32_e32 v60, v0
	v_mov_b32_e32 v61, v0
	v_mov_b32_e32 v62, v0
	v_mov_b32_e32 v63, v0
	s_waitcnt vmcnt(0)
	v_mov_b32_e32 v64, v0
	v_mov_b32_e32 v65, v0
	v_mov_b32_e32 v66, v0
	v_mov_b32_e32 v67, v0
	v_mov_b32_e32 v68, v0
	v_mov_b32_e32 v69, v0
	v_mov_b32_e32 v70, v0
	v_mov_b32_e32 v71, v0
	v_mov_b32_e32 v96, v0
	v_mov_b32_e32 v97, v0
	v_mov_b32_e32 v98, v0
	v_mov_b32_e32 v99, v0
	v_mov_b32_e32 v100, v0
	v_mov_b32_e32 v101, v0
	v_mov_b32_e32 v102, v0
	v_mov_b32_e32 v103, v0
	v_mov_b32_e32 v128, v0
	v_mov_b32_e32 v129, v0
	v_mov_b32_e32 v130, v0
	v_mov_b32_e32 v131, v0
	v_mov_b32_e32 v132, v0
	v_mov_b32_e32 v133, v0
	v_mov_b32_e32 v134, v0
	v_mov_b32_e32 v135, v0
	v_mov_b32_e32 v160, v0
	v_mov_b32_e32 v161, v0
	v_mov_b32_e32 v162, v0
	v_mov_b32_e32 v163, v0
	v_mov_b32_e32 v164, v0
	v_mov_b32_e32 v165, v0
	v_mov_b32_e32 v166, v0
	v_mov_b32_e32 v167, v0
	v_mov_b32_e32 v88, v0
	v_mov_b32_e32 v89, v0
	v_mov_b32_e32 v90, v0
	v_mov_b32_e32 v91, v0
	v_mov_b32_e32 v92, v0
	v_mov_b32_e32 v93, v0
	v_mov_b32_e32 v94, v0
	v_mov_b32_e32 v95, v0
	v_mov_b32_e32 v120, v0
	v_mov_b32_e32 v121, v0
	v_mov_b32_e32 v122, v0
	v_mov_b32_e32 v123, v0
	v_mov_b32_e32 v124, v0
	v_mov_b32_e32 v125, v0
	v_mov_b32_e32 v126, v0
	v_mov_b32_e32 v127, v0
	v_mov_b32_e32 v152, v0
	v_mov_b32_e32 v153, v0
	v_mov_b32_e32 v154, v0
	v_mov_b32_e32 v155, v0
	v_mov_b32_e32 v156, v0
	v_mov_b32_e32 v157, v0
	v_mov_b32_e32 v158, v0
	v_mov_b32_e32 v159, v0
	v_mov_b32_e32 v184, v0
	v_mov_b32_e32 v185, v0
	v_mov_b32_e32 v186, v0
	v_mov_b32_e32 v187, v0
	v_mov_b32_e32 v188, v0
	v_mov_b32_e32 v189, v0
	v_mov_b32_e32 v190, v0
	v_mov_b32_e32 v191, v0

; #define GAS __attribute__((address_space(1)))
; DI int lane_id_opaque() { int l; asm volatile("v_mbcnt_lo_u32_b32 %0, -1, 0\n\tv_mbcnt_hi_u32_b32 %0, -1, %0" : "=v"(l)); return l; }
;     DI void operator()(AccRef acc, const pg8::Unit& u, int wr, int wc, int, int) const {
;         const int lane_ = lane_id_opaque(), fr = lane_ & 15, fq = lane_ >> 4;
;         const int pn = u.pn;
;         const int kind = dummy ? 2 : (kind_force >= 0 ? kind_force : (pn < 6 ? (pn < 3 ? 0 : 1) : (pn < 15 ? 2 : (pn < 19 ? 3 : 4))));
;         const bool rot = (kind < 2) && ((wc & 1) == 0);
;         const float qs = (kind == 0) ? 0.125f : 1.0f;
;         EPI_PRELOAD_RSTD(ssq)
; #pragma unroll
;         for (int ai = 0; ai < 2; ++ai) {
;         f32x4 rc0[4], rc1[4], rs0[4], rs1[4];
; #pragma unroll
;         for (int m = 0; m < 4; ++m) { rc0[m] = (f32x4){1.f, 1.f, 1.f, 1.f}; rc1[m] = rc0[m]; rs0[m] = (f32x4){0.f, 0.f, 0.f, 0.f}; rs1[m] = rs0[m]; }
;         if (rot) {
; #pragma unroll
;             for (int m = 0; m < 4; ++m) { const GAS f32x4* rp = (const GAS f32x4*)(rope + (size_t)(u.pm * 256 + ai * 128 + wr * 64 + m * 16 + fr) * 16); rc0[m] = rp[0]; rc1[m] = rp[1]; rs0[m] = rp[2]; rs1[m] = rp[3]; }
.LBB0_825:
	s_cmp_eq_u32 s8, 2
	s_cbranch_scc1 .Llean_F_entry
	s_cmp_eq_u32 s8, 4
	s_cbranch_scc1 .Llean_F_entry
	v_and_or_b32 v72, v226, 15, s49
	v_ashrrev_i32_e32 v245, 4, v226
	v_lshl_add_u32 v224, s6, 8, v72
	v_lshlrev_b32_e32 v72, 2, v245
	v_or_b32_e32 v222, 16, v224
	v_ashrrev_i32_e32 v73, 31, v72
	v_ashrrev_i32_e32 v225, 31, v224
	v_ashrrev_i32_e32 v223, 31, v222
	v_lshl_add_u64 v[140:141], v[72:73], 2, s[26:27]
	v_lshlrev_b64 v[78:79], 6, v[224:225]
	v_lshlrev_b64 v[76:77], 6, v[222:223]
	v_or_b32_e32 v220, 32, v224
	v_or_b32_e32 v218, 48, v224
	v_lshl_add_u64 v[72:73], v[140:141], 0, v[78:79]
	v_lshl_add_u64 v[74:75], v[140:141], 0, v[76:77]
	v_ashrrev_i32_e32 v221, 31, v220
	v_ashrrev_i32_e32 v219, 31, v218
	v_add_u32_e32 v214, 0x80, v224
	global_load_dwordx4 v[80:83], v[72:73], off
	global_load_dwordx4 v[84:87], v[74:75], off
	v_lshlrev_b64 v[74:75], 6, v[220:221]
	v_lshlrev_b64 v[72:73], 6, v[218:219]
	v_ashrrev_i32_e32 v215, 31, v214
	v_lshl_add_u64 v[104:105], v[140:141], 0, v[74:75]
	v_lshl_add_u64 v[108:109], v[140:141], 0, v[72:73]
	v_lshlrev_b64 v[216:217], 6, v[214:215]
	global_load_dwordx4 v[104:107], v[104:105], off
	s_nop 0
	global_load_dwordx4 v[108:111], v[108:109], off
	v_lshl_add_u64 v[112:113], v[140:141], 0, v[216:217]
	global_load_dwordx4 v[112:115], v[112:113], off
	v_add_u32_e32 v212, 0x90, v224
	v_add_u32_e32 v210, 0xa0, v224
	v_add_u32_e32 v208, 0xb0, v224
	v_ashrrev_i32_e32 v213, 31, v212
	v_ashrrev_i32_e32 v211, 31, v210
	v_ashrrev_i32_e32 v209, 31, v208
	v_lshlrev_b64 v[116:117], 6, v[212:213]
	v_lshlrev_b64 v[136:137], 6, v[210:211]
	v_lshlrev_b64 v[142:143], 6, v[208:209]
	v_lshl_add_u64 v[116:117], v[140:141], 0, v[116:117]
	v_lshl_add_u64 v[136:137], v[140:141], 0, v[136:137]
	v_lshl_add_u64 v[140:141], v[140:141], 0, v[142:143]
	global_load_dwordx4 v[116:119], v[116:117], off
	s_cmp_gt_u32 s8, 1
	global_load_dwordx4 v[136:139], v[136:137], off
	s_cselect_b64 s[84:85], -1, 0
	global_load_dwordx4 v[140:143], v[140:141], off
	s_cmp_lt_u32 s8, 2
	s_cselect_b64 s[0:1], -1, 0
	s_and_b64 s[0:1], s[96:97], s[0:1]
	v_mov_b32_e32 v228, 0x260
	v_mov_b64_e32 v[242:243], 0x200
	s_andn2_b64 vcc, exec, s[0:1]
	s_waitcnt vmcnt(0)
	v_add_f32_e32 v80, v80, v81
	v_add_f32_e32 v81, v82, v83
	v_add_f32_e32 v80, v80, v81
	v_add_f32_e32 v81, v84, v85
	v_add_f32_e32 v82, v86, v87
	v_add_f32_e32 v81, v81, v82
	v_add_f32_e32 v83, v104, v105
	v_add_f32_e32 v84, v106, v107
	v_add_f32_e32 v85, v108, v109
	v_add_f32_e32 v86, v110, v111
	v_add_f32_e32 v87, v112, v113
	v_add_f32_e32 v104, v114, v115
	v_add_f32_e32 v82, v83, v84
	v_add_f32_e32 v83, v85, v86
	ds_swizzle_b32 v107, v80 offset:swizzle(SWAP,16)
	v_add_f32_e32 v84, v87, v104
	ds_swizzle_b32 v86, v81 offset:swizzle(SWAP,16)
	ds_swizzle_b32 v87, v82 offset:swizzle(SWAP,16)
	ds_swizzle_b32 v104, v83 offset:swizzle(SWAP,16)
	s_waitcnt lgkmcnt(3)
	v_add_f32_e32 v225, v80, v107
	v_mov_b32_e32 v227, v225
	s_waitcnt lgkmcnt(2)
	v_add_f32_e32 v252, v81, v86
	v_add_f32_e32 v105, v116, v117
	v_add_f32_e32 v106, v118, v119
	s_waitcnt lgkmcnt(1)
	v_add_f32_e32 v250, v82, v87
	s_waitcnt lgkmcnt(0)
	v_add_f32_e32 v248, v83, v104
	v_add_f32_e32 v80, v136, v137
	v_add_f32_e32 v81, v138, v139
	v_add_f32_e32 v82, v140, v141
	v_add_f32_e32 v83, v142, v143
	v_add_f32_e32 v85, v105, v106
	v_add_f32_e32 v80, v80, v81
	v_add_f32_e32 v82, v82, v83
	ds_swizzle_b32 v105, v84 offset:swizzle(SWAP,16)
	ds_swizzle_b32 v106, v85 offset:swizzle(SWAP,16)
	ds_swizzle_b32 v81, v80 offset:swizzle(SWAP,16)
	ds_swizzle_b32 v83, v82 offset:swizzle(SWAP,16)
	v_mov_b32_e32 v244, v252
	s_waitcnt lgkmcnt(3)
	v_add_f32_e32 v223, v84, v105
	s_waitcnt lgkmcnt(2)
	v_add_f32_e32 v219, v85, v106
	s_waitcnt lgkmcnt(1)
	v_add_f32_e32 v213, v80, v81
	s_waitcnt lgkmcnt(0)
	v_add_f32_e32 v209, v82, v83
	v_mov_b32_e32 v251, v250
	v_mov_b32_e32 v249, v248
	v_mov_b32_e32 v247, v223
	v_mov_b32_e32 v221, v219
	v_mov_b32_e32 v215, v213
	v_mov_b32_e32 v211, v209
	v_cndmask_b32_e64 v80, 0, 1, s[0:1]
	v_permlane32_swap_b32_e32 v225, v227
	v_permlane32_swap_b32_e32 v252, v244
	v_permlane32_swap_b32_e32 v250, v251
	v_permlane32_swap_b32_e32 v248, v249
	v_permlane32_swap_b32_e32 v223, v247
	v_permlane32_swap_b32_e32 v219, v221
	v_permlane32_swap_b32_e32 v213, v215
	v_permlane32_swap_b32_e32 v209, v211
	v_cmp_ne_u32_e64 s[6:7], 1, v80
	s_cbranch_vccnz .LBB0_827
	v_lshl_add_u64 v[78:79], s[56:57], 0, v[78:79]
	v_lshl_add_u64 v[76:77], s[56:57], 0, v[76:77]
	v_lshl_add_u64 v[74:75], s[56:57], 0, v[74:75]
	v_lshl_add_u64 v[84:85], s[56:57], 0, v[72:73]
	global_load_dwordx4 v[176:179], v[78:79], off offset:32
	global_load_dwordx4 v[168:171], v[78:79], off offset:48
	global_load_dwordx4 v[172:175], v[78:79], off offset:16
	global_load_dwordx4 v[180:183], v[78:79], off
	global_load_dwordx4 v[144:147], v[76:77], off offset:32
	global_load_dwordx4 v[136:139], v[76:77], off offset:48
	global_load_dwordx4 v[140:143], v[76:77], off offset:16
	global_load_dwordx4 v[148:151], v[76:77], off
	global_load_dwordx4 v[108:111], v[74:75], off offset:32
	global_load_dwordx4 v[104:107], v[74:75], off offset:48
	global_load_dwordx4 v[112:115], v[74:75], off offset:16
	global_load_dwordx4 v[116:119], v[74:75], off
	global_load_dwordx4 v[80:83], v[84:85], off offset:32
	global_load_dwordx4 v[76:79], v[84:85], off offset:48
	s_nop 0
	global_load_dwordx4 v[72:75], v[84:85], off offset:16
	s_nop 0
	global_load_dwordx4 v[84:87], v[84:85], off
	s_branch .LBB0_828
